# stack26 + seam 4 (P4->P5) replaced by a dataflow handshake: A1 stores written through, per-row-panel arrival counters, each workgroup waits only for the 16 producers of its own P5 row panel (grid!=256
# speedup vs baseline: 1.0079x; 1.0079x over previous
.LBB0_706:
	s_cmp_gt_i32 s89, 5
	v_readlane_b32 s0, v246, 0
	s_cselect_b64 s[2:3], -1, 0
	v_readlane_b32 s1, v246, 1
	s_and_b64 s[0:1], s[0:1], s[2:3]
	s_andn2_b64 vcc, exec, s[0:1]
	s_cbranch_vccnz .LBB0_760
	s_waitcnt vmcnt(0)
	s_waitcnt vmcnt(0)
	s_barrier
	s_and_saveexec_b64 s[4:5], s[84:85]
	s_cbranch_execz .LBB0_759
	s_cmp_lg_u32 s79, 0x100
	s_cbranch_scc1 .Ldf4_full
	s_and_b32 s0, s78, 7
	s_lshl_b32 s0, s0, 5
	s_lshr_b32 s1, s78, 3
	s_add_i32 s0, s0, s1
	s_lshr_b32 s1, s0, 6
	s_lshl_b32 s1, s1, 3
	s_and_b32 s6, s0, 15
	s_lshr_b32 s7, s6, 2
	s_add_i32 s7, s7, s1
	s_sub_i32 s6, 31, s6
	s_lshr_b32 s6, s6, 2
	s_add_i32 s6, s6, s1
	s_and_b32 s98, s0, 7
	s_add_i32 s98, s98, s1
	s_lshl_b32 s6, s6, 8
	s_add_i32 s6, s6, 0xe000
	s_lshl_b32 s7, s7, 8
	s_add_i32 s7, s7, 0xe000
	s_lshl_b32 s98, s98, 8
	s_add_i32 s98, s98, 0xe000
	v_mov_b32_e32 v2, s6
	v_mov_b32_e32 v3, 1
	global_atomic_add v2, v3, s[76:77]
	v_mov_b32_e32 v4, s7
	global_atomic_add v4, v3, s[76:77]
	v_mov_b32_e32 v2, s98
	s_mov_b32 s99, 0
.Ldf4_poll:
	global_load_dword v4, v2, s[76:77] sc1
	s_waitcnt vmcnt(0)
	v_readfirstlane_b32 s0, v4
	s_cmp_ge_u32 s0, 16
	s_cbranch_scc1 .Ldf4_go
	s_sleep 1
	s_add_i32 s99, s99, 1
	s_cmp_lt_u32 s99, 0x100000
	s_cbranch_scc1 .Ldf4_poll
